# scan S-update MFMA chain software-pipelined (LDS reads double-buffered), bit-identical
# baseline (speedup 1.0000x reference)
.LBB0_554:
	s_nop 5
	v_lshl_add_u32 v132, v160, 2, 0
	v_add_u32_e32 v132, 0x20600, v132
	v_add_u32_e32 v133, 0, v163
	v_add_u32_e32 v142, v133, v161
	v_add_u32_e32 v143, v133, v162
	v_xad_u32 v144, v161, 64, v133
	v_xad_u32 v145, v162, 64, v133
	v_xad_u32 v146, v161, s74, v133
	v_xad_u32 v147, v162, s74, v133
	v_xad_u32 v148, v161, s54, v133
	v_xad_u32 v149, v162, s54, v133
	ds_read_b128 v[164:167], v132
	ds_read_b128 v[168:171], v132 offset:16
	ds_read_b64_tr_b16 v[172:173], v159
	ds_read_b64_tr_b16 v[174:175], v158 offset:1024
	ds_read_b64_tr_b16 v[98:99], v142 offset:32768
	ds_read_b64_tr_b16 v[100:101], v143 offset:33792
	ds_read_b64_tr_b16 v[102:103], v144 offset:32768
	ds_read_b64_tr_b16 v[104:105], v145 offset:33792
	ds_read_b64_tr_b16 v[106:107], v146 offset:32768
	ds_read_b64_tr_b16 v[108:109], v147 offset:33792
	ds_read_b64_tr_b16 v[110:111], v148 offset:32768
	ds_read_b64_tr_b16 v[112:113], v149 offset:33792
	v_pk_mul_f32 v[64:65], v[64:65], v[138:139] op_sel_hi:[1,0]
	v_pk_mul_f32 v[62:63], v[62:63], v[138:139] op_sel_hi:[1,0]
	v_pk_mul_f32 v[60:61], v[60:61], v[138:139] op_sel_hi:[1,0]
	v_pk_mul_f32 v[58:59], v[58:59], v[138:139] op_sel_hi:[1,0]
	v_pk_mul_f32 v[56:57], v[56:57], v[138:139] op_sel_hi:[1,0]
	v_pk_mul_f32 v[54:55], v[54:55], v[138:139] op_sel_hi:[1,0]
	v_pk_mul_f32 v[52:53], v[52:53], v[138:139] op_sel_hi:[1,0]
	v_pk_mul_f32 v[50:51], v[50:51], v[138:139] op_sel_hi:[1,0]
	v_pk_mul_f32 v[48:49], v[48:49], v[138:139] op_sel_hi:[1,0]
	v_pk_mul_f32 v[46:47], v[46:47], v[138:139] op_sel_hi:[1,0]
	v_pk_mul_f32 v[44:45], v[44:45], v[138:139] op_sel_hi:[1,0]
	v_pk_mul_f32 v[42:43], v[42:43], v[138:139] op_sel_hi:[1,0]
	v_pk_mul_f32 v[40:41], v[40:41], v[138:139] op_sel_hi:[1,0]
	v_pk_mul_f32 v[38:39], v[38:39], v[138:139] op_sel_hi:[1,0]
	v_pk_mul_f32 v[36:37], v[36:37], v[138:139] op_sel_hi:[1,0]
	v_pk_mul_f32 v[34:35], v[34:35], v[138:139] op_sel_hi:[1,0]
	v_pk_mul_f32 v[32:33], v[32:33], v[138:139] op_sel_hi:[1,0]
	v_pk_mul_f32 v[30:31], v[30:31], v[138:139] op_sel_hi:[1,0]
	v_pk_mul_f32 v[28:29], v[28:29], v[138:139] op_sel_hi:[1,0]
	v_pk_mul_f32 v[26:27], v[26:27], v[138:139] op_sel_hi:[1,0]
	v_pk_mul_f32 v[24:25], v[24:25], v[138:139] op_sel_hi:[1,0]
	v_pk_mul_f32 v[22:23], v[22:23], v[138:139] op_sel_hi:[1,0]
	v_pk_mul_f32 v[20:21], v[20:21], v[138:139] op_sel_hi:[1,0]
	v_pk_mul_f32 v[18:19], v[18:19], v[138:139] op_sel_hi:[1,0]
	v_pk_mul_f32 v[16:17], v[16:17], v[138:139] op_sel_hi:[1,0]
	v_pk_mul_f32 v[14:15], v[14:15], v[138:139] op_sel_hi:[1,0]
	v_pk_mul_f32 v[12:13], v[12:13], v[138:139] op_sel_hi:[1,0]
	v_pk_mul_f32 v[10:11], v[10:11], v[138:139] op_sel_hi:[1,0]
	v_pk_mul_f32 v[8:9], v[8:9], v[138:139] op_sel_hi:[1,0]
	v_pk_mul_f32 v[6:7], v[6:7], v[138:139] op_sel_hi:[1,0]
	v_pk_mul_f32 v[4:5], v[4:5], v[138:139] op_sel_hi:[1,0]
	v_pk_mul_f32 v[2:3], v[2:3], v[138:139] op_sel_hi:[1,0]
	s_waitcnt lgkmcnt(8)
	v_lshlrev_b32_e32 v224, 16, v172
	v_and_b32_e32 v225, 0xffff0000, v172
	v_lshlrev_b32_e32 v226, 16, v173
	v_and_b32_e32 v227, 0xffff0000, v173
	v_pk_mul_f32 v[220:221], v[164:165], v[224:225]
	v_pk_mul_f32 v[222:223], v[166:167], v[226:227]
	v_cvt_pk_bf16_f32 v196, v220, v221
	v_cvt_pk_bf16_f32 v197, v222, v223
	v_lshlrev_b32_e32 v224, 16, v174
	v_and_b32_e32 v225, 0xffff0000, v174
	v_lshlrev_b32_e32 v226, 16, v175
	v_and_b32_e32 v227, 0xffff0000, v175
	v_pk_mul_f32 v[220:221], v[168:169], v[224:225]
	v_pk_mul_f32 v[222:223], v[170:171], v[226:227]
	v_cvt_pk_bf16_f32 v198, v220, v221
	v_cvt_pk_bf16_f32 v199, v222, v223
	ds_read_b128 v[176:179], v132 offset:64
	ds_read_b128 v[180:183], v132 offset:80
	ds_read_b64_tr_b16 v[184:185], v159 offset:4096
	ds_read_b64_tr_b16 v[186:187], v158 offset:5120
	s_waitcnt lgkmcnt(4)
	v_mfma_f32_32x32x16_bf16 v[50:65], v[98:101], v[196:199], v[50:65]
	ds_read_b64_tr_b16 v[114:115], v142 offset:36864
	ds_read_b64_tr_b16 v[116:117], v143 offset:37888
	ds_read_b64_tr_b16 v[118:119], v144 offset:36864
	ds_read_b64_tr_b16 v[120:121], v145 offset:37888
	v_mfma_f32_32x32x16_bf16 v[34:49], v[102:105], v[196:199], v[34:49]
	ds_read_b64_tr_b16 v[122:123], v146 offset:36864
	ds_read_b64_tr_b16 v[124:125], v147 offset:37888
	ds_read_b64_tr_b16 v[126:127], v148 offset:36864
	ds_read_b64_tr_b16 v[128:129], v149 offset:37888
	s_waitcnt lgkmcnt(8)
	v_lshlrev_b32_e32 v224, 16, v184
	v_and_b32_e32 v225, 0xffff0000, v184
	v_lshlrev_b32_e32 v226, 16, v185
	v_and_b32_e32 v227, 0xffff0000, v185
	v_pk_mul_f32 v[220:221], v[176:177], v[224:225]
	v_pk_mul_f32 v[222:223], v[178:179], v[226:227]
	v_cvt_pk_bf16_f32 v200, v220, v221
	v_cvt_pk_bf16_f32 v201, v222, v223
	v_mfma_f32_32x32x16_bf16 v[18:33], v[106:109], v[196:199], v[18:33]
	v_lshlrev_b32_e32 v224, 16, v186
	v_and_b32_e32 v225, 0xffff0000, v186
	v_lshlrev_b32_e32 v226, 16, v187
	v_and_b32_e32 v227, 0xffff0000, v187
	v_pk_mul_f32 v[220:221], v[180:181], v[224:225]
	v_pk_mul_f32 v[222:223], v[182:183], v[226:227]
	v_cvt_pk_bf16_f32 v202, v220, v221
	v_cvt_pk_bf16_f32 v203, v222, v223
	v_mfma_f32_32x32x16_bf16 v[2:17], v[110:113], v[196:199], v[2:17]
	ds_read_b128 v[164:167], v132 offset:128
	ds_read_b128 v[168:171], v132 offset:144
	ds_read_b64_tr_b16 v[172:173], v159 offset:8192
	ds_read_b64_tr_b16 v[174:175], v158 offset:9216
	s_waitcnt lgkmcnt(4)
	v_mfma_f32_32x32x16_bf16 v[50:65], v[114:117], v[200:203], v[50:65]
	ds_read_b64_tr_b16 v[98:99], v142 offset:40960
	ds_read_b64_tr_b16 v[100:101], v143 offset:41984
	ds_read_b64_tr_b16 v[102:103], v144 offset:40960
	ds_read_b64_tr_b16 v[104:105], v145 offset:41984
	v_mfma_f32_32x32x16_bf16 v[34:49], v[118:121], v[200:203], v[34:49]
	ds_read_b64_tr_b16 v[106:107], v146 offset:40960
	ds_read_b64_tr_b16 v[108:109], v147 offset:41984
	ds_read_b64_tr_b16 v[110:111], v148 offset:40960
	ds_read_b64_tr_b16 v[112:113], v149 offset:41984
	s_waitcnt lgkmcnt(8)
	v_lshlrev_b32_e32 v224, 16, v172
	v_and_b32_e32 v225, 0xffff0000, v172
	v_lshlrev_b32_e32 v226, 16, v173
	v_and_b32_e32 v227, 0xffff0000, v173
	v_pk_mul_f32 v[220:221], v[164:165], v[224:225]
	v_pk_mul_f32 v[222:223], v[166:167], v[226:227]
	v_cvt_pk_bf16_f32 v196, v220, v221
	v_cvt_pk_bf16_f32 v197, v222, v223
	v_mfma_f32_32x32x16_bf16 v[18:33], v[122:125], v[200:203], v[18:33]
	v_lshlrev_b32_e32 v224, 16, v174
	v_and_b32_e32 v225, 0xffff0000, v174
	v_lshlrev_b32_e32 v226, 16, v175
	v_and_b32_e32 v227, 0xffff0000, v175
	v_pk_mul_f32 v[220:221], v[168:169], v[224:225]
	v_pk_mul_f32 v[222:223], v[170:171], v[226:227]
	v_cvt_pk_bf16_f32 v198, v220, v221
	v_cvt_pk_bf16_f32 v199, v222, v223
	v_mfma_f32_32x32x16_bf16 v[2:17], v[126:129], v[200:203], v[2:17]
	ds_read_b128 v[176:179], v132 offset:192
	ds_read_b128 v[180:183], v132 offset:208
	ds_read_b64_tr_b16 v[184:185], v159 offset:12288
	ds_read_b64_tr_b16 v[186:187], v158 offset:13312
	s_waitcnt lgkmcnt(4)
	v_mfma_f32_32x32x16_bf16 v[50:65], v[98:101], v[196:199], v[50:65]
	ds_read_b64_tr_b16 v[114:115], v142 offset:45056
	ds_read_b64_tr_b16 v[116:117], v143 offset:46080
	ds_read_b64_tr_b16 v[118:119], v144 offset:45056
	ds_read_b64_tr_b16 v[120:121], v145 offset:46080
	v_mfma_f32_32x32x16_bf16 v[34:49], v[102:105], v[196:199], v[34:49]
	ds_read_b64_tr_b16 v[122:123], v146 offset:45056
	ds_read_b64_tr_b16 v[124:125], v147 offset:46080
	ds_read_b64_tr_b16 v[126:127], v148 offset:45056
	ds_read_b64_tr_b16 v[128:129], v149 offset:46080
	s_waitcnt lgkmcnt(8)
	v_lshlrev_b32_e32 v224, 16, v184
	v_and_b32_e32 v225, 0xffff0000, v184
	v_lshlrev_b32_e32 v226, 16, v185
	v_and_b32_e32 v227, 0xffff0000, v185
	v_pk_mul_f32 v[220:221], v[176:177], v[224:225]
	v_pk_mul_f32 v[222:223], v[178:179], v[226:227]
	v_cvt_pk_bf16_f32 v200, v220, v221
	v_cvt_pk_bf16_f32 v201, v222, v223
	v_mfma_f32_32x32x16_bf16 v[18:33], v[106:109], v[196:199], v[18:33]
	v_lshlrev_b32_e32 v224, 16, v186
	v_and_b32_e32 v225, 0xffff0000, v186
	v_lshlrev_b32_e32 v226, 16, v187
	v_and_b32_e32 v227, 0xffff0000, v187
	v_pk_mul_f32 v[220:221], v[180:181], v[224:225]
	v_pk_mul_f32 v[222:223], v[182:183], v[226:227]
	v_cvt_pk_bf16_f32 v202, v220, v221
	v_cvt_pk_bf16_f32 v203, v222, v223
	v_mfma_f32_32x32x16_bf16 v[2:17], v[110:113], v[196:199], v[2:17]
	ds_read_b128 v[164:167], v132 offset:256
	ds_read_b128 v[168:171], v132 offset:272
	ds_read_b64_tr_b16 v[172:173], v159 offset:16384
	ds_read_b64_tr_b16 v[174:175], v158 offset:17408
	s_waitcnt lgkmcnt(4)
	v_mfma_f32_32x32x16_bf16 v[50:65], v[114:117], v[200:203], v[50:65]
	ds_read_b64_tr_b16 v[98:99], v142 offset:49152
	ds_read_b64_tr_b16 v[100:101], v143 offset:50176
	ds_read_b64_tr_b16 v[102:103], v144 offset:49152
	ds_read_b64_tr_b16 v[104:105], v145 offset:50176
	v_mfma_f32_32x32x16_bf16 v[34:49], v[118:121], v[200:203], v[34:49]
	ds_read_b64_tr_b16 v[106:107], v146 offset:49152
	ds_read_b64_tr_b16 v[108:109], v147 offset:50176
	ds_read_b64_tr_b16 v[110:111], v148 offset:49152
	ds_read_b64_tr_b16 v[112:113], v149 offset:50176
	s_waitcnt lgkmcnt(8)
	v_lshlrev_b32_e32 v224, 16, v172
	v_and_b32_e32 v225, 0xffff0000, v172
	v_lshlrev_b32_e32 v226, 16, v173
	v_and_b32_e32 v227, 0xffff0000, v173
	v_pk_mul_f32 v[220:221], v[164:165], v[224:225]
	v_pk_mul_f32 v[222:223], v[166:167], v[226:227]
	v_cvt_pk_bf16_f32 v196, v220, v221
	v_cvt_pk_bf16_f32 v197, v222, v223
	v_mfma_f32_32x32x16_bf16 v[18:33], v[122:125], v[200:203], v[18:33]
	v_lshlrev_b32_e32 v224, 16, v174
	v_and_b32_e32 v225, 0xffff0000, v174
	v_lshlrev_b32_e32 v226, 16, v175
	v_and_b32_e32 v227, 0xffff0000, v175
	v_pk_mul_f32 v[220:221], v[168:169], v[224:225]
	v_pk_mul_f32 v[222:223], v[170:171], v[226:227]
	v_cvt_pk_bf16_f32 v198, v220, v221
	v_cvt_pk_bf16_f32 v199, v222, v223
	v_mfma_f32_32x32x16_bf16 v[2:17], v[126:129], v[200:203], v[2:17]
	ds_read_b128 v[176:179], v132 offset:320
	ds_read_b128 v[180:183], v132 offset:336
	ds_read_b64_tr_b16 v[184:185], v159 offset:20480
	ds_read_b64_tr_b16 v[186:187], v158 offset:21504
	s_waitcnt lgkmcnt(4)
	v_mfma_f32_32x32x16_bf16 v[50:65], v[98:101], v[196:199], v[50:65]
	ds_read_b64_tr_b16 v[114:115], v142 offset:53248
	ds_read_b64_tr_b16 v[116:117], v143 offset:54272
	ds_read_b64_tr_b16 v[118:119], v144 offset:53248
	ds_read_b64_tr_b16 v[120:121], v145 offset:54272
	v_mfma_f32_32x32x16_bf16 v[34:49], v[102:105], v[196:199], v[34:49]
	ds_read_b64_tr_b16 v[122:123], v146 offset:53248
	ds_read_b64_tr_b16 v[124:125], v147 offset:54272
	ds_read_b64_tr_b16 v[126:127], v148 offset:53248
	ds_read_b64_tr_b16 v[128:129], v149 offset:54272
	s_waitcnt lgkmcnt(8)
	v_lshlrev_b32_e32 v224, 16, v184
	v_and_b32_e32 v225, 0xffff0000, v184
	v_lshlrev_b32_e32 v226, 16, v185
	v_and_b32_e32 v227, 0xffff0000, v185
	v_pk_mul_f32 v[220:221], v[176:177], v[224:225]
	v_pk_mul_f32 v[222:223], v[178:179], v[226:227]
	v_cvt_pk_bf16_f32 v200, v220, v221
	v_cvt_pk_bf16_f32 v201, v222, v223
	v_mfma_f32_32x32x16_bf16 v[18:33], v[106:109], v[196:199], v[18:33]
	v_lshlrev_b32_e32 v224, 16, v186
	v_and_b32_e32 v225, 0xffff0000, v186
	v_lshlrev_b32_e32 v226, 16, v187
	v_and_b32_e32 v227, 0xffff0000, v187
	v_pk_mul_f32 v[220:221], v[180:181], v[224:225]
	v_pk_mul_f32 v[222:223], v[182:183], v[226:227]
	v_cvt_pk_bf16_f32 v202, v220, v221
	v_cvt_pk_bf16_f32 v203, v222, v223
	v_mfma_f32_32x32x16_bf16 v[2:17], v[110:113], v[196:199], v[2:17]
	ds_read_b128 v[164:167], v132 offset:384
	ds_read_b128 v[168:171], v132 offset:400
	ds_read_b64_tr_b16 v[172:173], v159 offset:24576
	ds_read_b64_tr_b16 v[174:175], v158 offset:25600
	s_waitcnt lgkmcnt(4)
	v_mfma_f32_32x32x16_bf16 v[50:65], v[114:117], v[200:203], v[50:65]
	ds_read_b64_tr_b16 v[98:99], v142 offset:57344
	ds_read_b64_tr_b16 v[100:101], v143 offset:58368
	ds_read_b64_tr_b16 v[102:103], v144 offset:57344
	ds_read_b64_tr_b16 v[104:105], v145 offset:58368
	v_mfma_f32_32x32x16_bf16 v[34:49], v[118:121], v[200:203], v[34:49]
	ds_read_b64_tr_b16 v[106:107], v146 offset:57344
	ds_read_b64_tr_b16 v[108:109], v147 offset:58368
	ds_read_b64_tr_b16 v[110:111], v148 offset:57344
	ds_read_b64_tr_b16 v[112:113], v149 offset:58368
	s_waitcnt lgkmcnt(8)
	v_lshlrev_b32_e32 v224, 16, v172
	v_and_b32_e32 v225, 0xffff0000, v172
	v_lshlrev_b32_e32 v226, 16, v173
	v_and_b32_e32 v227, 0xffff0000, v173
	v_pk_mul_f32 v[220:221], v[164:165], v[224:225]
	v_pk_mul_f32 v[222:223], v[166:167], v[226:227]
	v_cvt_pk_bf16_f32 v196, v220, v221
	v_cvt_pk_bf16_f32 v197, v222, v223
	v_mfma_f32_32x32x16_bf16 v[18:33], v[122:125], v[200:203], v[18:33]
	v_lshlrev_b32_e32 v224, 16, v174
	v_and_b32_e32 v225, 0xffff0000, v174
	v_lshlrev_b32_e32 v226, 16, v175
	v_and_b32_e32 v227, 0xffff0000, v175
	v_pk_mul_f32 v[220:221], v[168:169], v[224:225]
	v_pk_mul_f32 v[222:223], v[170:171], v[226:227]
	v_cvt_pk_bf16_f32 v198, v220, v221
	v_cvt_pk_bf16_f32 v199, v222, v223
	v_mfma_f32_32x32x16_bf16 v[2:17], v[126:129], v[200:203], v[2:17]
	ds_read_b128 v[176:179], v132 offset:448
	ds_read_b128 v[180:183], v132 offset:464
	ds_read_b64_tr_b16 v[184:185], v159 offset:28672
	ds_read_b64_tr_b16 v[186:187], v158 offset:29696
	s_waitcnt lgkmcnt(4)
	v_mfma_f32_32x32x16_bf16 v[50:65], v[98:101], v[196:199], v[50:65]
	ds_read_b64_tr_b16 v[114:115], v142 offset:61440
	ds_read_b64_tr_b16 v[116:117], v143 offset:62464
	ds_read_b64_tr_b16 v[118:119], v144 offset:61440
	ds_read_b64_tr_b16 v[120:121], v145 offset:62464
	v_mfma_f32_32x32x16_bf16 v[34:49], v[102:105], v[196:199], v[34:49]
	ds_read_b64_tr_b16 v[122:123], v146 offset:61440
	ds_read_b64_tr_b16 v[124:125], v147 offset:62464
	ds_read_b64_tr_b16 v[126:127], v148 offset:61440
	ds_read_b64_tr_b16 v[128:129], v149 offset:62464
	s_waitcnt lgkmcnt(8)
	v_lshlrev_b32_e32 v224, 16, v184
	v_and_b32_e32 v225, 0xffff0000, v184
	v_lshlrev_b32_e32 v226, 16, v185
	v_and_b32_e32 v227, 0xffff0000, v185
	v_pk_mul_f32 v[220:221], v[176:177], v[224:225]
	v_pk_mul_f32 v[222:223], v[178:179], v[226:227]
	v_cvt_pk_bf16_f32 v200, v220, v221
	v_cvt_pk_bf16_f32 v201, v222, v223
	v_mfma_f32_32x32x16_bf16 v[18:33], v[106:109], v[196:199], v[18:33]
	v_lshlrev_b32_e32 v224, 16, v186
	v_and_b32_e32 v225, 0xffff0000, v186
	v_lshlrev_b32_e32 v226, 16, v187
	v_and_b32_e32 v227, 0xffff0000, v187
	v_pk_mul_f32 v[220:221], v[180:181], v[224:225]
	v_pk_mul_f32 v[222:223], v[182:183], v[226:227]
	v_cvt_pk_bf16_f32 v202, v220, v221
	v_cvt_pk_bf16_f32 v203, v222, v223
	v_mfma_f32_32x32x16_bf16 v[2:17], v[110:113], v[196:199], v[2:17]
	s_waitcnt lgkmcnt(0)
	s_and_b64 vcc, exec, s[6:7]
	v_mfma_f32_32x32x16_bf16 v[50:65], v[114:117], v[200:203], v[50:65]
	v_mfma_f32_32x32x16_bf16 v[34:49], v[118:121], v[200:203], v[34:49]
	v_mfma_f32_32x32x16_bf16 v[18:33], v[122:125], v[200:203], v[18:33]
	v_mfma_f32_32x32x16_bf16 v[2:17], v[126:129], v[200:203], v[2:17]
	s_cbranch_vccnz .LBB0_558
	v_ashrrev_i32_e32 v66, 2, v140
	v_lshrrev_b32_e32 v68, 2, v66
	v_and_b32_e32 v67, -4, v66
	v_bitop3_b32 v68, v68, v156, 3 bitop3:0x6c
	v_lshlrev_b32_e32 v70, 8, v67
	v_lshlrev_b32_e32 v68, 4, v68
	s_add_i32 s8, 0, 0x20600
	v_bfe_u32 v69, v66, 2, 2
	v_add3_u32 v68, 0, v68, v70
	v_lshl_add_u32 v67, v67, 2, s8
	ds_read_b128 v[72:75], v68 offset:32768
	ds_read_b96 v[106:108], v67
	v_bitop3_b32 v67, v69, v156, 4 bitop3:0x36
	v_bitop3_b32 v68, v69, v156, 8 bitop3:0x36
	v_lshlrev_b32_e32 v67, 4, v67
	v_lshlrev_b32_e32 v68, 4, v68
	v_add3_u32 v67, 0, v67, v70
	v_add3_u32 v68, 0, v68, v70
	ds_read_b128 v[76:79], v67 offset:33024
	ds_read_b128 v[98:101], v68 offset:33280
	v_or_b32_e32 v66, 3, v66
	v_bitop3_b32 v68, v69, v156, 12 bitop3:0x36
	v_lshlrev_b32_e32 v67, 8, v66
	v_lshlrev_b32_e32 v68, 4, v68
	v_add3_u32 v67, 0, v68, v67
	v_lshl_add_u32 v66, v66, 2, s8
	ds_read_b128 v[102:105], v67 offset:32768
	ds_read_b32 v80, v66
	s_waitcnt lgkmcnt(5)
	v_lshlrev_b32_e32 v66, 16, v72
	v_and_b32_e32 v67, 0xffff0000, v72
	v_lshlrev_b32_e32 v70, 16, v73
	v_and_b32_e32 v71, 0xffff0000, v73
	s_waitcnt lgkmcnt(4)
	v_pk_fma_f32 v[66:67], v[106:107], v[66:67], 0 op_sel_hi:[0,1,0]
	s_waitcnt lgkmcnt(3)
	v_lshlrev_b32_e32 v68, 16, v76
	v_and_b32_e32 v69, 0xffff0000, v76
	v_pk_fma_f32 v[70:71], v[106:107], v[70:71], 0 op_sel_hi:[0,1,0]
	v_lshlrev_b32_e32 v72, 16, v77
	v_and_b32_e32 v73, 0xffff0000, v77
	v_pk_fma_f32 v[66:67], v[106:107], v[68:69], v[66:67] op_sel:[1,0,0]
	s_waitcnt lgkmcnt(2)
	v_lshlrev_b32_e32 v68, 16, v98
	v_and_b32_e32 v69, 0xffff0000, v98
	v_mov_b32_e32 v76, v108
	v_pk_fma_f32 v[70:71], v[106:107], v[72:73], v[70:71] op_sel:[1,0,0]
	v_lshlrev_b32_e32 v72, 16, v99
	v_and_b32_e32 v73, 0xffff0000, v99
	v_lshlrev_b32_e32 v98, 16, v74
	v_and_b32_e32 v99, 0xffff0000, v74
	v_lshlrev_b32_e32 v74, 16, v75
	v_and_b32_e32 v75, 0xffff0000, v75
	v_pk_fma_f32 v[66:67], v[76:77], v[68:69], v[66:67] op_sel_hi:[0,1,1]
	s_waitcnt lgkmcnt(1)
	v_lshlrev_b32_e32 v68, 16, v102
	v_and_b32_e32 v69, 0xffff0000, v102
	v_pk_fma_f32 v[70:71], v[76:77], v[72:73], v[70:71] op_sel_hi:[0,1,1]
	v_lshlrev_b32_e32 v72, 16, v103
	v_and_b32_e32 v73, 0xffff0000, v103
	v_pk_fma_f32 v[98:99], v[106:107], v[98:99], 0 op_sel_hi:[0,1,0]
	v_lshlrev_b32_e32 v102, 16, v78
	v_and_b32_e32 v103, 0xffff0000, v78
	v_pk_fma_f32 v[74:75], v[106:107], v[74:75], 0 op_sel_hi:[0,1,0]
	v_lshlrev_b32_e32 v78, 16, v79
	v_and_b32_e32 v79, 0xffff0000, v79
	v_pk_fma_f32 v[98:99], v[106:107], v[102:103], v[98:99] op_sel:[1,0,0]
	v_lshlrev_b32_e32 v102, 16, v100
	v_and_b32_e32 v103, 0xffff0000, v100
	v_pk_fma_f32 v[74:75], v[106:107], v[78:79], v[74:75] op_sel:[1,0,0]
	v_lshlrev_b32_e32 v78, 16, v101
	v_and_b32_e32 v79, 0xffff0000, v101
	v_pk_fma_f32 v[98:99], v[76:77], v[102:103], v[98:99] op_sel_hi:[0,1,1]
	v_lshlrev_b32_e32 v102, 16, v104
	v_and_b32_e32 v103, 0xffff0000, v104
	v_pk_fma_f32 v[74:75], v[76:77], v[78:79], v[74:75] op_sel_hi:[0,1,1]
	v_lshlrev_b32_e32 v76, 16, v105
	v_and_b32_e32 v77, 0xffff0000, v105
	s_waitcnt lgkmcnt(0)
	v_pk_fma_f32 v[66:67], v[80:81], v[68:69], v[66:67] op_sel_hi:[0,1,1]
	v_pk_fma_f32 v[70:71], v[80:81], v[72:73], v[70:71] op_sel_hi:[0,1,1]
	v_pk_fma_f32 v[98:99], v[80:81], v[102:103], v[98:99] op_sel_hi:[0,1,1]
	v_pk_fma_f32 v[78:79], v[80:81], v[76:77], v[74:75] op_sel_hi:[0,1,1]
	ds_swizzle_b32 v68, v66 offset:swizzle(SWAP,16)
	ds_swizzle_b32 v69, v67 offset:swizzle(SWAP,16)
	ds_swizzle_b32 v72, v70 offset:swizzle(SWAP,16)
	ds_swizzle_b32 v73, v71 offset:swizzle(SWAP,16)
	ds_swizzle_b32 v102, v98 offset:swizzle(SWAP,16)
	ds_swizzle_b32 v103, v99 offset:swizzle(SWAP,16)
	ds_swizzle_b32 v80, v78 offset:swizzle(SWAP,16)
	ds_swizzle_b32 v81, v79 offset:swizzle(SWAP,16)
	s_waitcnt lgkmcnt(6)
	v_pk_add_f32 v[66:67], v[66:67], v[68:69]
	s_waitcnt lgkmcnt(4)
	v_pk_add_f32 v[70:71], v[70:71], v[72:73]
	s_waitcnt lgkmcnt(2)
	v_pk_add_f32 v[74:75], v[98:99], v[102:103]
	ds_bpermute_b32 v68, v157, v66
	s_waitcnt lgkmcnt(1)
	v_pk_add_f32 v[78:79], v[78:79], v[80:81]
	ds_bpermute_b32 v69, v157, v67
	ds_bpermute_b32 v72, v157, v70
	ds_bpermute_b32 v73, v157, v71
	ds_bpermute_b32 v76, v157, v74
	ds_bpermute_b32 v77, v157, v75
	ds_bpermute_b32 v80, v157, v78
	ds_bpermute_b32 v81, v157, v79
	v_cmp_gt_u32_e32 vcc, 16, v155
	s_and_saveexec_b64 s[8:9], vcc
	s_cbranch_execz .LBB0_557
	v_readlane_b32 s10, v254, 53
	s_waitcnt lgkmcnt(6)
	v_pk_add_f32 v[66:67], v[66:67], v[68:69]
	s_waitcnt lgkmcnt(4)
	v_pk_add_f32 v[68:69], v[70:71], v[72:73]
	v_lshl_add_u32 v98, v156, 5, s10
	ds_write_b128 v98, v[66:69]
	s_waitcnt lgkmcnt(3)
	v_pk_add_f32 v[66:67], v[74:75], v[76:77]
	s_waitcnt lgkmcnt(1)
	v_pk_add_f32 v[68:69], v[78:79], v[80:81]
	ds_write_b128 v98, v[66:69] offset:16
